# DFT stage-2 items software-pipelined: next same-type item's 4 staging loads issued as the youngest loads of the current item (MFMA-section waits shifted by 4), consumed from registers at the next item
# speedup vs baseline: 1.0006x; 1.0006x over previous
; template <int STAGE>
; __device__ void dft_phase(const bf16_t* src, bf16_t* dst, const bf16_t* DT, LAS unsigned char* lds) {
;   for (int it = blockIdx.x; it < 2048; it += gridDim.x) {
;     if (it < 1024) dft_item<STAGE>(src, dst, DT + DT_C128, DT + DT_S128, 128, 7, 16384, it >> 3, it & 7, 16384, 128, 128, lds);
;     else {
;       const int r = it - 1024, b = r >> 7, rr = r & 127;
;       if (STAGE == 1) dft_item<STAGE>(src, dst, DT + DT_C32, DT + DT_S32, 32, 5, b * 2048, rr >> 1, rr & 1, 2048, 32, 64, lds);
;       else dft_item<STAGE>(src, dst, DT + DT_C64, DT + DT_S64, 64, 6, b * 2048, rr >> 2, rr & 3, 2048, 32, 64, lds);
;     }
;   }
.LBB0_506:
	s_waitcnt vmcnt(0)
	v_readlane_b32 s6, v252, 45
	v_readlane_b32 s7, v252, 46
	s_andn2_b64 vcc, exec, s[6:7]
	s_mov_b32 s6, s2
	v_readlane_b32 s7, v250, 16
	v_readlane_b32 s12, v255, 37
	s_mov_b32 s13, s2
	s_cbranch_vccz .LBB0_516

; #define LAS __attribute__((address_space(3)))
; template <int STAGE>
; __device__ void dft_item(const bf16_t* __restrict__ src, bf16_t* __restrict__ dst, const bf16_t* __restrict__ Ct, const bf16_t* __restrict__ St,
;                          int N, int lgN, int rowbase, int j, int chblk, int S, int N1, int N2, LAS unsigned char* lds) {
;     ...
;     const int q = tid + it * 512, n = q >> lgcpr, cq = q & (cpr - 1), part = cq >> (lgcpr - 1), cc = cq & ((cpr >> 1) - 1);
;     const int irow = STAGE == 1 ? rowbase + N2 * n + j : rowbase + j * N2 + n;
;     const u32x4 v = *(const u32x4*)(src + (size_t)irow * 1024 + part * 512 + chblk * CB + cc * 8);
;     *(LAS u32x4*)(lds + n * stride + (part * CB + cc * 8) * 2) = v;
;   }
; template <int STAGE>
; __device__ void dft_phase(const bf16_t* src, bf16_t* dst, const bf16_t* DT, LAS unsigned char* lds) {
;   for (int it = blockIdx.x; it < 2048; it += gridDim.x) {
;     if (it < 1024) dft_item<STAGE>(src, dst, DT + DT_C128, DT + DT_S128, 128, 7, 16384, it >> 3, it & 7, 16384, 128, 128, lds);
;     else {
;       const int r = it - 1024, b = r >> 7, rr = r & 127;
;       if (STAGE == 1) dft_item<STAGE>(src, dst, DT + DT_C32, DT + DT_S32, 32, 5, b * 2048, rr >> 1, rr & 1, 2048, 32, 64, lds);
;       else dft_item<STAGE>(src, dst, DT + DT_C64, DT + DT_S64, 64, 6, b * 2048, rr >> 2, rr & 3, 2048, 32, 64, lds);
.LBB0_511:
	s_cmpk_gt_i32 s13, 0x3ff
	s_mov_b64 s[22:23], -1
	s_cbranch_scc0 .LBB0_513
	v_mov_b32_e32 v20, v214
	s_and_b32 s23, s12, 0x7ffff800
	s_bfe_u32 s22, s13, 0x50002
	s_addk_i32 s23, 0xc000
	v_lshlrev_b32_e32 v2, 4, v20
	s_lshl_b32 s20, s22, 6
	v_and_b32_e32 v16, 0xf0, v2
	v_add_u32_e32 v2, 0x200, v20
	v_add_u32_e32 v8, 0x400, v20
	v_add_u32_e32 v10, 0x600, v20
	s_or_b32 s35, s20, s23
	v_ashrrev_i32_e32 v18, 5, v20
	v_ashrrev_i32_e32 v21, 5, v2
	v_ashrrev_i32_e32 v22, 5, v8
	v_ashrrev_i32_e32 v23, 5, v10
	v_add_u32_e32 v0, s35, v18
	v_add_u32_e32 v2, s35, v21
	v_add_u32_e32 v8, s35, v22
	v_add_u32_e32 v10, s35, v23
	v_ashrrev_i32_e32 v1, 31, v0
	v_ashrrev_i32_e32 v3, 31, v2
	v_ashrrev_i32_e32 v9, 31, v8
	v_ashrrev_i32_e32 v11, 31, v10
	v_bfe_u32 v19, v20, 4, 1
	v_lshlrev_b64 v[0:1], 11, v[0:1]
	v_lshlrev_b64 v[2:3], 11, v[2:3]
	v_lshlrev_b64 v[8:9], 11, v[8:9]
	v_lshlrev_b64 v[10:11], 11, v[10:11]
	s_and_b32 s34, s7, 0x180
	v_lshl_add_u64 v[0:1], s[10:11], 0, v[0:1]
	v_lshlrev_b32_e32 v160, 10, v19
	v_lshl_add_u64 v[2:3], s[10:11], 0, v[2:3]
	v_lshl_add_u64 v[8:9], s[10:11], 0, v[8:9]
	v_lshl_add_u64 v[10:11], s[10:11], 0, v[10:11]
	v_lshl_add_u64 v[0:1], v[0:1], 0, v[160:161]
	s_lshl_b32 s20, s34, 1
	v_lshl_add_u64 v[2:3], v[2:3], 0, v[160:161]
	v_lshl_add_u64 v[8:9], v[8:9], 0, v[160:161]
	v_lshl_add_u64 v[10:11], v[10:11], 0, v[160:161]
	v_lshl_add_u64 v[0:1], v[0:1], 0, s[20:21]
	v_mov_b32_e32 v17, v161
	v_lshl_add_u64 v[2:3], v[2:3], 0, s[20:21]
	v_lshl_add_u64 v[8:9], v[8:9], 0, s[20:21]
	v_lshl_add_u64 v[10:11], v[10:11], 0, s[20:21]
	v_lshl_add_u64 v[0:1], v[0:1], 0, v[16:17]
	v_lshl_add_u64 v[4:5], v[2:3], 0, v[16:17]
	v_lshl_add_u64 v[8:9], v[8:9], 0, v[16:17]
	v_lshl_add_u64 v[12:13], v[10:11], 0, v[16:17]
	v_readlane_b32 s71, v255, 29
	s_add_i32 s71, s12, s71
	s_add_i32 s74, s13, s90
	v_readlane_b32 s75, v255, 36
	s_add_i32 s75, s7, s75
	s_mov_b64 s[72:73], 0
	s_cmpk_lt_i32 s74, 0x800
	s_cbranch_scc0 .Ldpf_go_C
	s_and_b32 s71, s71, 0x7ffff800
	s_addk_i32 s71, 0xc000
	s_bfe_u32 s74, s74, 0x50002
	s_lshl_b32 s74, s74, 6
	s_or_b32 s71, s74, s71
	s_sub_i32 s72, s71, s35
	s_ashr_i32 s73, s72, 31
	s_lshl_b64 s[72:73], s[72:73], 11
	s_and_b32 s75, s75, 0x180
	s_sub_i32 s75, s75, s34
	s_lshl_b32 s75, s75, 1
	s_ashr_i32 s76, s75, 31
	s_add_u32 s72, s72, s75
	s_addc_u32 s73, s73, s76
.Ldpf_go_C:
	s_cmp_eq_u32 s69, 2
	s_cbranch_scc1 .Lswp_have_2
	s_waitcnt vmcnt(0)
	v_lshl_add_u64 v[114:115], v[0:1], 0, s[72:73]
	v_lshl_add_u64 v[118:119], v[4:5], 0, s[72:73]
	v_lshl_add_u64 v[122:123], v[8:9], 0, s[72:73]
	v_lshl_add_u64 v[126:127], v[12:13], 0, s[72:73]
	global_load_dwordx4 v[0:3], v[0:1], off
	s_nop 0
	global_load_dwordx4 v[4:7], v[4:5], off
	s_nop 0
	global_load_dwordx4 v[8:11], v[8:9], off
	s_nop 0
	global_load_dwordx4 v[12:15], v[12:13], off
.Lswp_have_2:
	v_and_b32_e32 v17, 31, v20
	v_lshrrev_b32_e32 v24, 1, v20
	v_mul_lo_u32 v18, v18, s54
	v_lshlrev_b32_e32 v19, 8, v19
	v_and_or_b32 v42, v24, 32, v17
	v_add_u32_e32 v17, 0, v18
	v_mul_lo_u32 v18, v21, s54
	v_mul_lo_u32 v21, v22, s54
	v_mul_lo_u32 v22, v23, s54
	v_readlane_b32 s36, v252, 41
	v_add3_u32 v23, v17, v19, v16
	v_add_u32_e32 v17, 0, v18
	v_add_u32_e32 v18, 0, v21
	v_add_u32_e32 v21, 0, v22
	v_lshlrev_b32_e32 v160, 7, v42
	v_readlane_b32 s37, v252, 42
	v_mov_b32_e32 v37, v161
	v_and_b32_e32 v36, 16, v24
	v_add3_u32 v22, v17, v19, v16
	v_add3_u32 v18, v18, v19, v16
	v_add3_u32 v19, v21, v19, v16
	v_lshl_add_u64 v[16:17], s[36:37], 0, v[160:161]
	v_lshl_add_u64 v[38:39], v[16:17], 0, v[36:37]
	v_readlane_b32 s36, v252, 43
	v_readlane_b32 s37, v252, 44
	s_cmp_eq_u32 s69, 2
	s_cbranch_scc1 .Ldtskip_2
	v_lshl_add_u64 v[210:211], s[36:37], 0, v[160:161]
	v_lshl_add_u64 v[40:41], v[210:211], 0, v[36:37]
	global_load_dwordx4 v[50:53], v[38:39], off
	global_load_dwordx4 v[54:57], v[40:41], off
	global_load_dwordx4 v[58:61], v[38:39], off offset:32
	global_load_dwordx4 v[62:65], v[40:41], off offset:32
	global_load_dwordx4 v[66:69], v[38:39], off offset:64
	global_load_dwordx4 v[70:73], v[40:41], off offset:64
	global_load_dwordx4 v[74:77], v[38:39], off offset:96
	global_load_dwordx4 v[78:81], v[40:41], off offset:96
	s_mov_b32 s69, 2
	global_load_dwordx4 v[114:117], v[114:115], off
	global_load_dwordx4 v[118:121], v[118:119], off
	global_load_dwordx4 v[122:125], v[122:123], off
	global_load_dwordx4 v[126:129], v[126:127], off
	s_waitcnt vmcnt(15)
	ds_write_b128 v23, v[0:3]
	s_waitcnt vmcnt(14)
	ds_write_b128 v22, v[4:7]
	s_waitcnt vmcnt(13)
	ds_write_b128 v18, v[8:11]
	s_waitcnt vmcnt(12)
	ds_write_b128 v19, v[12:15]
	s_branch .Ldtjoin_2
.Ldtskip_2:
	s_waitcnt vmcnt(2)
	ds_write_b128 v23, v[114:117]
	ds_write_b128 v22, v[118:121]
	ds_write_b128 v18, v[122:125]
	ds_write_b128 v19, v[126:129]
	s_waitcnt lgkmcnt(0)
	v_lshl_add_u64 v[114:115], v[0:1], 0, s[72:73]
	v_lshl_add_u64 v[118:119], v[4:5], 0, s[72:73]
	v_lshl_add_u64 v[122:123], v[8:9], 0, s[72:73]
	v_lshl_add_u64 v[126:127], v[12:13], 0, s[72:73]
	global_load_dwordx4 v[114:117], v[114:115], off
	global_load_dwordx4 v[118:121], v[118:119], off
	global_load_dwordx4 v[122:125], v[122:123], off
	global_load_dwordx4 v[126:129], v[126:127], off
; template <int STAGE>
; __device__ void dft_item(const bf16_t* __restrict__ src, bf16_t* __restrict__ dst, const bf16_t* __restrict__ Ct, const bf16_t* __restrict__ St,
;                          int N, int lgN, int rowbase, int j, int chblk, int S, int N1, int N2, LAS unsigned char* lds) {
;     ...
; #pragma unroll
;   for (int it = 0; it < 4; ++it) {
;     const int q = tid + it * 512, n = q >> lgcpr, cq = q & (cpr - 1), part = cq >> (lgcpr - 1), cc = cq & ((cpr >> 1) - 1);
;     const int irow = STAGE == 1 ? rowbase + N2 * n + j : rowbase + j * N2 + n;
;     const u32x4 v = *(const u32x4*)(src + (size_t)irow * 1024 + part * 512 + chblk * CB + cc * 8);
;     ...
;   const int kts = N >> 5, kt = w & (kts - 1), chsub = w >> (lgN - 5);
;   const int i16 = l & 15, q4 = i16 >> 2, p4 = i16 & 3, G1 = (l >> 4) & 1, h = l >> 5;
;   const unsigned colre = (unsigned)(chsub * 32 + 16 * G1 + 4 * p4) * 2u, colim = colre + (unsigned)CB * 2u;
;   const int kout = kt * 32 + (l & 31);
;   f32x16 a0 = {}, a1 = {}, a2 = {};
;   const int nks = N >> 4;
;   bf16x8 Bc[8], Bs[8];
; #pragma unroll
;   for (int ks = 0; ks < 8; ++ks) if (ks < nks) { Bc[ks] = *(const bf16x8*)(Ct + kout * N + 16 * ks + 8 * h); Bs[ks] = *(const bf16x8*)(St + kout * N + 16 * ks + 8 * h); }
; #pragma unroll
;   for (int ks = 0; ks < 8; ++ks) if (ks < nks) {
;     const unsigned rlo = (unsigned)(16 * ks + 8 * h + q4) * stride, rhi = rlo + 4u * stride;
;     const bf16x8 Ar = tr_frag(lds, rlo + colre, rhi + colre), Ai = tr_frag(lds, rlo + colim, rhi + colim);
;     a0 = mfma32(Ar, Bc[ks], a0); a0 = mfma32(Ai, Bs[ks], a0);
;     if (STAGE == 1) { a1 = mfma32(Ai, Bc[ks], a1); a2 = mfma32(Ar, Bs[ks], a2); }
;   }
;   const int chb = chblk * CB + chsub * 32;
;   if (STAGE == 1) {
;     const int mm = (j * kout) & (S - 1); const float fr = (float)mm / (float)S;
;     const float c = __builtin_amdgcn_cosf(fr), s = __builtin_amdgcn_sinf(fr);
;     const size_t orow = (size_t)(rowbase + kout * N2 + j) * 1024;
;     f32x16 re, im;
; #pragma unroll
;     for (int i = 0; i < 16; ++i) { const float yr = a0[i], yi = a1[i] - a2[i]; re[i] = yr * c + yi * s; im[i] = yi * c - yr * s; }
;     store_tile16(dst + orow + chb, re, 1.f, h); store_tile16(dst + orow + 512 + chb, im, 1.f, h);
;   } else {
;     const size_t orow = (size_t)(rowbase + j + N1 * kout) * 512;
;     store_tile16(dst + orow + chb, a0, 1.f, h);
;   }
;   __syncthreads();
.Ldtjoin_2:
	s_waitcnt lgkmcnt(0)
	s_barrier
	v_lshrrev_b32_e32 v4, 2, v20
	v_and_b32_e32 v5, 16, v20
	v_ashrrev_i32_e32 v6, 2, v20
	v_lshlrev_b32_e32 v7, 2, v20
	v_and_b32_e32 v43, 0xffffffe0, v6
	v_and_b32_e32 v6, 12, v7
	v_and_b32_e32 v4, 11, v4
	v_or3_b32 v5, v5, v6, v43
	v_mul_u32_u24_e32 v4, 0x240, v4
	v_lshlrev_b32_e32 v5, 1, v5
	v_add3_u32 v44, 0, v5, v4
	ds_read_b64_tr_b16 v[4:5], v44
	ds_read_b64_tr_b16 v[6:7], v44 offset:2304
	ds_read_b64_tr_b16 v[30:31], v44 offset:2560
	ds_read_b64_tr_b16 v[28:29], v44 offset:256
	s_waitcnt vmcnt(11) lgkmcnt(2)
	v_mfma_f32_32x32x16_bf16 v[0:15], v[4:7], v[50:53], 0
	s_waitcnt vmcnt(10) lgkmcnt(0)
	v_mfma_f32_32x32x16_bf16 v[0:15], v[28:31], v[54:57], v[0:15]
	ds_read_b64_tr_b16 v[16:17], v44 offset:9216
	ds_read_b64_tr_b16 v[18:19], v44 offset:11520
	ds_read_b64_tr_b16 v[30:31], v44 offset:11776
	ds_read_b64_tr_b16 v[28:29], v44 offset:9472
	s_waitcnt vmcnt(9) lgkmcnt(2)
	v_mfma_f32_32x32x16_bf16 v[0:15], v[16:19], v[58:61], v[0:15]
	ds_read_b64_tr_b16 v[20:21], v44 offset:18432
	ds_read_b64_tr_b16 v[22:23], v44 offset:20736
	s_waitcnt vmcnt(8) lgkmcnt(2)
	v_mfma_f32_32x32x16_bf16 v[0:15], v[28:31], v[62:65], v[0:15]
	ds_read_b64_tr_b16 v[30:31], v44 offset:20992
	ds_read_b64_tr_b16 v[28:29], v44 offset:18688
	s_waitcnt vmcnt(7) lgkmcnt(2)
	v_mfma_f32_32x32x16_bf16 v[0:15], v[20:23], v[66:69], v[0:15]
	v_add_u32_e32 v32, s34, v43
	v_ashrrev_i32_e32 v33, 31, v32
	s_waitcnt vmcnt(6) lgkmcnt(0)
	v_mfma_f32_32x32x16_bf16 v[0:15], v[28:31], v[70:73], v[0:15]
	ds_read_b64_tr_b16 v[16:17], v44 offset:27648
	ds_read_b64_tr_b16 v[18:19], v44 offset:29952
	ds_read_b64_tr_b16 v[30:31], v44 offset:30208
	ds_read_b64_tr_b16 v[28:29], v44 offset:27904
	s_waitcnt vmcnt(5) lgkmcnt(2)
	v_mfma_f32_32x32x16_bf16 v[0:15], v[16:19], v[74:77], v[0:15]
	v_lshl_or_b32 v16, v42, 5, s23
	v_or_b32_e32 v160, s22, v16
	v_readlane_b32 s22, v253, 3
	v_lshlrev_b64 v[16:17], 10, v[160:161]
	v_readlane_b32 s23, v253, 4
	s_waitcnt vmcnt(4) lgkmcnt(0)
	v_mfma_f32_32x32x16_bf16 v[0:15], v[28:31], v[78:81], v[0:15]
	v_lshl_add_u64 v[16:17], s[22:23], 0, v[16:17]
	v_lshl_add_u64 v[16:17], v[32:33], 1, v[16:17]
	v_lshl_add_u64 v[16:17], v[16:17], 0, v[36:37]
	s_mov_b64 s[22:23], 0
	s_nop 7
	v_cvt_pk_bf16_f32 v0, v0, v1
	v_cvt_pk_bf16_f32 v1, v2, v3
	v_cvt_pk_bf16_f32 v2, v4, v5
	v_cvt_pk_bf16_f32 v3, v6, v7
	v_cvt_pk_bf16_f32 v4, v8, v9
	v_cvt_pk_bf16_f32 v5, v10, v11
	v_cvt_pk_bf16_f32 v6, v12, v13
	v_cvt_pk_bf16_f32 v7, v14, v15
	v_permlane32_swap_b32_e32 v0, v2
	v_permlane32_swap_b32_e32 v1, v3
	v_permlane32_swap_b32_e32 v4, v6
	v_permlane32_swap_b32_e32 v5, v7
	global_store_dwordx4 v[16:17], v[0:3], off
	global_store_dwordx4 v[16:17], v[4:7], off offset:32
	s_barrier
.LBB0_513:
	s_andn2_b64 vcc, exec, s[22:23]
	s_cbranch_vccnz .LBB0_510
	v_mov_b32_e32 v22, v214
	s_ashr_i32 s22, s13, 3
	s_lshl_b32 s20, s22, 7
	v_lshlrev_b32_e32 v2, 4, v22
	v_and_b32_e32 v18, 0x70, v2
	v_add_u32_e32 v2, 0x200, v22
	v_add_u32_e32 v8, 0x400, v22
	v_add_u32_e32 v10, 0x600, v22
	s_add_i32 s34, s20, 0x4000
	v_ashrrev_i32_e32 v16, 4, v22
	v_ashrrev_i32_e32 v21, 4, v2
	v_ashrrev_i32_e32 v23, 4, v8
	v_ashrrev_i32_e32 v24, 4, v10
	v_add_u32_e32 v0, s34, v16
	v_add_u32_e32 v2, s34, v21
	v_add_u32_e32 v8, s34, v23
	v_add_u32_e32 v10, s34, v24
	v_ashrrev_i32_e32 v1, 31, v0
	v_ashrrev_i32_e32 v3, 31, v2
	v_ashrrev_i32_e32 v9, 31, v8
	v_ashrrev_i32_e32 v11, 31, v10
	v_bfe_u32 v20, v22, 3, 1
	v_lshlrev_b64 v[0:1], 11, v[0:1]
	v_lshlrev_b64 v[2:3], 11, v[2:3]
	v_lshlrev_b64 v[8:9], 11, v[8:9]
	v_lshlrev_b64 v[10:11], 11, v[10:11]
	s_and_b32 s23, s6, 0x1c0
	v_lshl_add_u64 v[0:1], s[10:11], 0, v[0:1]
	v_lshlrev_b32_e32 v160, 10, v20
	v_lshl_add_u64 v[2:3], s[10:11], 0, v[2:3]
	v_lshl_add_u64 v[8:9], s[10:11], 0, v[8:9]
	v_lshl_add_u64 v[10:11], s[10:11], 0, v[10:11]
	v_lshl_add_u64 v[0:1], v[0:1], 0, v[160:161]
	s_lshl_b32 s20, s23, 1
	v_lshl_add_u64 v[2:3], v[2:3], 0, v[160:161]
	v_lshl_add_u64 v[8:9], v[8:9], 0, v[160:161]
	v_lshl_add_u64 v[10:11], v[10:11], 0, v[160:161]
	v_lshl_add_u64 v[0:1], v[0:1], 0, s[20:21]
	v_mov_b32_e32 v19, v161
	v_lshl_add_u64 v[2:3], v[2:3], 0, s[20:21]
	v_lshl_add_u64 v[8:9], v[8:9], 0, s[20:21]
	v_lshl_add_u64 v[10:11], v[10:11], 0, s[20:21]
	v_lshl_add_u64 v[0:1], v[0:1], 0, v[18:19]
	v_lshl_add_u64 v[4:5], v[2:3], 0, v[18:19]
	v_lshl_add_u64 v[8:9], v[8:9], 0, v[18:19]
	v_lshl_add_u64 v[12:13], v[10:11], 0, v[18:19]
	s_add_i32 s74, s13, s90
	s_add_i32 s75, s6, s33
	s_mov_b64 s[72:73], 0
	s_cmpk_lt_i32 s74, 0x400
	s_cbranch_scc0 .Ldpf_go_D
	s_ashr_i32 s71, s74, 3
	s_lshl_b32 s71, s71, 7
	s_add_i32 s71, s71, 0x4000
	s_sub_i32 s72, s71, s34
	s_ashr_i32 s73, s72, 31
	s_lshl_b64 s[72:73], s[72:73], 11
	s_and_b32 s75, s75, 0x1c0
	s_sub_i32 s75, s75, s23
	s_lshl_b32 s75, s75, 1
	s_ashr_i32 s76, s75, 31
	s_add_u32 s72, s72, s75
	s_addc_u32 s73, s73, s76
.Ldpf_go_D:
	s_cmp_eq_u32 s69, 1
	s_cbranch_scc1 .Lswp_have_1
	s_waitcnt vmcnt(0)
	v_lshl_add_u64 v[114:115], v[0:1], 0, s[72:73]
	v_lshl_add_u64 v[118:119], v[4:5], 0, s[72:73]
	v_lshl_add_u64 v[122:123], v[8:9], 0, s[72:73]
	v_lshl_add_u64 v[126:127], v[12:13], 0, s[72:73]
	global_load_dwordx4 v[0:3], v[0:1], off
	s_nop 0
	global_load_dwordx4 v[4:7], v[4:5], off
	s_nop 0
	global_load_dwordx4 v[8:11], v[8:9], off
	s_nop 0
	global_load_dwordx4 v[12:15], v[12:13], off
; #define LAS __attribute__((address_space(3)))
; template <int STAGE>
; __device__ void dft_item(const bf16_t* __restrict__ src, bf16_t* __restrict__ dst, const bf16_t* __restrict__ Ct, const bf16_t* __restrict__ St,
;                          int N, int lgN, int rowbase, int j, int chblk, int S, int N1, int N2, LAS unsigned char* lds) {
;     ...
; #pragma unroll
;   for (int it = 0; it < 4; ++it) {
;     const int q = tid + it * 512, n = q >> lgcpr, cq = q & (cpr - 1), part = cq >> (lgcpr - 1), cc = cq & ((cpr >> 1) - 1);
;     const int irow = STAGE == 1 ? rowbase + N2 * n + j : rowbase + j * N2 + n;
;     const u32x4 v = *(const u32x4*)(src + (size_t)irow * 1024 + part * 512 + chblk * CB + cc * 8);
;     *(LAS u32x4*)(lds + n * stride + (part * CB + cc * 8) * 2) = v;
;   }
;   __syncthreads();
;   const int kts = N >> 5, kt = w & (kts - 1), chsub = w >> (lgN - 5);
;   const int i16 = l & 15, q4 = i16 >> 2, p4 = i16 & 3, G1 = (l >> 4) & 1, h = l >> 5;
;   const unsigned colre = (unsigned)(chsub * 32 + 16 * G1 + 4 * p4) * 2u, colim = colre + (unsigned)CB * 2u;
;   const int kout = kt * 32 + (l & 31);
;   f32x16 a0 = {}, a1 = {}, a2 = {};
;   const int nks = N >> 4;
;   bf16x8 Bc[8], Bs[8];
; #pragma unroll
;   for (int ks = 0; ks < 8; ++ks) if (ks < nks) { Bc[ks] = *(const bf16x8*)(Ct + kout * N + 16 * ks + 8 * h); Bs[ks] = *(const bf16x8*)(St + kout * N + 16 * ks + 8 * h); }
.Lswp_have_1:
	s_movk_i32 s20, 0x140
	v_lshrrev_b32_e32 v19, 1, v22
	v_and_b32_e32 v25, 31, v22
	v_mul_lo_u32 v26, v16, s20
	v_lshlrev_b32_e32 v20, 7, v20
	v_and_or_b32 v46, v19, s77, v25
	v_and_b32_e32 v16, 16, v19
	v_add_u32_e32 v19, 0, v26
	v_mul_lo_u32 v21, v21, s20
	v_mul_lo_u32 v23, v23, s20
	v_mul_lo_u32 v24, v24, s20
	v_readlane_b32 s34, v250, 49
	v_add3_u32 v25, v19, v20, v18
	v_add_u32_e32 v19, 0, v21
	v_add_u32_e32 v21, 0, v23
	v_add_u32_e32 v23, 0, v24
	v_lshlrev_b32_e32 v160, 8, v46
	v_readlane_b32 s35, v250, 50
	v_mov_b32_e32 v17, v161
	v_add3_u32 v24, v19, v20, v18
	v_add3_u32 v21, v21, v20, v18
	v_add3_u32 v20, v23, v20, v18
	v_lshl_add_u64 v[18:19], s[34:35], 0, v[160:161]
	v_lshl_add_u64 v[42:43], v[18:19], 0, v[16:17]
	v_readlane_b32 s34, v252, 37
	v_readlane_b32 s35, v252, 38
	s_addk_i32 s22, 0x4000
	s_cmp_eq_u32 s69, 1
	s_cbranch_scc1 .Ldtskip_1
	v_lshl_add_u64 v[210:211], s[34:35], 0, v[160:161]
	v_lshl_add_u64 v[44:45], v[210:211], 0, v[16:17]
	global_load_dwordx4 v[50:53], v[42:43], off
	global_load_dwordx4 v[54:57], v[44:45], off
	global_load_dwordx4 v[58:61], v[42:43], off offset:32
	global_load_dwordx4 v[62:65], v[44:45], off offset:32
	global_load_dwordx4 v[66:69], v[42:43], off offset:64
	global_load_dwordx4 v[70:73], v[44:45], off offset:64
	global_load_dwordx4 v[74:77], v[42:43], off offset:96
	global_load_dwordx4 v[78:81], v[44:45], off offset:96
	global_load_dwordx4 v[82:85], v[42:43], off offset:128
	global_load_dwordx4 v[86:89], v[44:45], off offset:128
	global_load_dwordx4 v[90:93], v[42:43], off offset:160
	global_load_dwordx4 v[94:97], v[44:45], off offset:160
	global_load_dwordx4 v[98:101], v[42:43], off offset:192
	global_load_dwordx4 v[102:105], v[44:45], off offset:192
	global_load_dwordx4 v[106:109], v[42:43], off offset:224
	global_load_dwordx4 v[110:113], v[44:45], off offset:224
	s_mov_b32 s69, 1
	global_load_dwordx4 v[114:117], v[114:115], off
	global_load_dwordx4 v[118:121], v[118:119], off
	global_load_dwordx4 v[122:125], v[122:123], off
	global_load_dwordx4 v[126:129], v[126:127], off
	s_waitcnt vmcnt(23)
	ds_write_b128 v25, v[0:3]
	s_waitcnt vmcnt(22)
	ds_write_b128 v24, v[4:7]
	s_waitcnt vmcnt(21)
	ds_write_b128 v21, v[8:11]
	s_waitcnt vmcnt(20)
	ds_write_b128 v20, v[12:15]
	s_branch .Ldtjoin_1
.Ldtskip_1:
	s_waitcnt vmcnt(2)
	ds_write_b128 v25, v[114:117]
	ds_write_b128 v24, v[118:121]
	ds_write_b128 v21, v[122:125]
	ds_write_b128 v20, v[126:129]
	s_waitcnt lgkmcnt(0)
	v_lshl_add_u64 v[114:115], v[0:1], 0, s[72:73]
	v_lshl_add_u64 v[118:119], v[4:5], 0, s[72:73]
	v_lshl_add_u64 v[122:123], v[8:9], 0, s[72:73]
	v_lshl_add_u64 v[126:127], v[12:13], 0, s[72:73]
	global_load_dwordx4 v[114:117], v[114:115], off
	global_load_dwordx4 v[118:121], v[118:119], off
	global_load_dwordx4 v[122:125], v[122:123], off
	global_load_dwordx4 v[126:129], v[126:127], off
; __device__ __forceinline__ f32x16 mfma32(bf16x8 a, bf16x8 b, f32x16 c) { return __builtin_amdgcn_mfma_f32_32x32x16_bf16(a, b, c, 0, 0, 0); }
; template <int STAGE>
; __device__ void dft_item(const bf16_t* __restrict__ src, bf16_t* __restrict__ dst, const bf16_t* __restrict__ Ct, const bf16_t* __restrict__ St,
;                          int N, int lgN, int rowbase, int j, int chblk, int S, int N1, int N2, LAS unsigned char* lds) {
;     ...
; #pragma unroll
;   for (int ks = 0; ks < 8; ++ks) if (ks < nks) { Bc[ks] = *(const bf16x8*)(Ct + kout * N + 16 * ks + 8 * h); Bs[ks] = *(const bf16x8*)(St + kout * N + 16 * ks + 8 * h); }
; #pragma unroll
;   for (int ks = 0; ks < 8; ++ks) if (ks < nks) {
;     const unsigned rlo = (unsigned)(16 * ks + 8 * h + q4) * stride, rhi = rlo + 4u * stride;
;     const bf16x8 Ar = tr_frag(lds, rlo + colre, rhi + colre), Ai = tr_frag(lds, rlo + colim, rhi + colim);
;     a0 = mfma32(Ar, Bc[ks], a0); a0 = mfma32(Ai, Bs[ks], a0);
;     if (STAGE == 1) { a1 = mfma32(Ai, Bc[ks], a1); a2 = mfma32(Ar, Bs[ks], a2); }
;   }
;   const int chb = chblk * CB + chsub * 32;
;   if (STAGE == 1) {
;     const int mm = (j * kout) & (S - 1); const float fr = (float)mm / (float)S;
;     const float c = __builtin_amdgcn_cosf(fr), s = __builtin_amdgcn_sinf(fr);
;     const size_t orow = (size_t)(rowbase + kout * N2 + j) * 1024;
;     f32x16 re, im;
; #pragma unroll
;     for (int i = 0; i < 16; ++i) { const float yr = a0[i], yi = a1[i] - a2[i]; re[i] = yr * c + yi * s; im[i] = yi * c - yr * s; }
;     store_tile16(dst + orow + chb, re, 1.f, h); store_tile16(dst + orow + 512 + chb, im, 1.f, h);
;   } else {
;     const size_t orow = (size_t)(rowbase + j + N1 * kout) * 512;
;     store_tile16(dst + orow + chb, a0, 1.f, h);
;   }
;   __syncthreads();
.Ldtjoin_1:
	s_waitcnt lgkmcnt(0)
	s_barrier
	v_lshrrev_b32_e32 v4, 2, v22
	v_and_b32_e32 v5, 16, v22
	v_ashrrev_i32_e32 v6, 3, v22
	v_lshlrev_b32_e32 v7, 2, v22
	v_and_b32_e32 v47, 0xffffffe0, v6
	v_and_b32_e32 v6, 12, v7
	v_and_b32_e32 v4, 11, v4
	v_or3_b32 v5, v5, v6, v47
	v_mul_u32_u24_e32 v4, 0x140, v4
	v_lshlrev_b32_e32 v5, 1, v5
	v_add3_u32 v48, 0, v5, v4
	ds_read_b64_tr_b16 v[4:5], v48
	ds_read_b64_tr_b16 v[6:7], v48 offset:1280
	ds_read_b64_tr_b16 v[32:33], v48 offset:1408
	ds_read_b64_tr_b16 v[30:31], v48 offset:128
	s_waitcnt vmcnt(19) lgkmcnt(2)
	v_mfma_f32_32x32x16_bf16 v[0:15], v[4:7], v[50:53], 0
	s_waitcnt vmcnt(18) lgkmcnt(0)
	v_mfma_f32_32x32x16_bf16 v[0:15], v[30:33], v[54:57], v[0:15]
	ds_read_b64_tr_b16 v[18:19], v48 offset:5120
	ds_read_b64_tr_b16 v[20:21], v48 offset:6400
	ds_read_b64_tr_b16 v[32:33], v48 offset:6528
	ds_read_b64_tr_b16 v[30:31], v48 offset:5248
	s_waitcnt vmcnt(17) lgkmcnt(2)
	v_mfma_f32_32x32x16_bf16 v[0:15], v[18:21], v[58:61], v[0:15]
	ds_read_b64_tr_b16 v[22:23], v48 offset:10240
	ds_read_b64_tr_b16 v[24:25], v48 offset:11520
	s_waitcnt vmcnt(16) lgkmcnt(2)
	v_mfma_f32_32x32x16_bf16 v[0:15], v[30:33], v[62:65], v[0:15]
	ds_read_b64_tr_b16 v[32:33], v48 offset:11648
	ds_read_b64_tr_b16 v[30:31], v48 offset:10368
	s_waitcnt vmcnt(15) lgkmcnt(2)
	v_mfma_f32_32x32x16_bf16 v[0:15], v[22:25], v[66:69], v[0:15]
	s_waitcnt vmcnt(14) lgkmcnt(0)
	v_mfma_f32_32x32x16_bf16 v[0:15], v[30:33], v[70:73], v[0:15]
	ds_read_b64_tr_b16 v[30:31], v48 offset:15360
	ds_read_b64_tr_b16 v[32:33], v48 offset:16640
	ds_read_b64_tr_b16 v[40:41], v48 offset:16768
	ds_read_b64_tr_b16 v[38:39], v48 offset:15488
	s_waitcnt vmcnt(13) lgkmcnt(2)
	v_mfma_f32_32x32x16_bf16 v[0:15], v[30:33], v[74:77], v[0:15]
	ds_read_b64_tr_b16 v[30:31], v48 offset:20480
	ds_read_b64_tr_b16 v[32:33], v48 offset:21760
	s_waitcnt vmcnt(12) lgkmcnt(2)
	v_mfma_f32_32x32x16_bf16 v[0:15], v[38:41], v[78:81], v[0:15]
	ds_read_b64_tr_b16 v[40:41], v48 offset:21888
	ds_read_b64_tr_b16 v[38:39], v48 offset:20608
	s_waitcnt vmcnt(11) lgkmcnt(2)
	v_mfma_f32_32x32x16_bf16 v[0:15], v[30:33], v[82:85], v[0:15]
	s_waitcnt vmcnt(10) lgkmcnt(0)
	v_mfma_f32_32x32x16_bf16 v[0:15], v[38:41], v[86:89], v[0:15]
	ds_read_b64_tr_b16 v[30:31], v48 offset:25600
	ds_read_b64_tr_b16 v[32:33], v48 offset:26880
	ds_read_b64_tr_b16 v[36:37], v48 offset:27008
	ds_read_b64_tr_b16 v[34:35], v48 offset:25728
	s_waitcnt vmcnt(9) lgkmcnt(2)
	v_mfma_f32_32x32x16_bf16 v[0:15], v[30:33], v[90:93], v[0:15]
	ds_read_b64_tr_b16 v[30:31], v48 offset:30720
	ds_read_b64_tr_b16 v[32:33], v48 offset:32000
	s_waitcnt vmcnt(8) lgkmcnt(2)
	v_mfma_f32_32x32x16_bf16 v[0:15], v[34:37], v[94:97], v[0:15]
	ds_read_b64_tr_b16 v[36:37], v48 offset:32128
	ds_read_b64_tr_b16 v[34:35], v48 offset:30848
	s_waitcnt vmcnt(7) lgkmcnt(2)
	v_mfma_f32_32x32x16_bf16 v[0:15], v[30:33], v[98:101], v[0:15]
	s_waitcnt vmcnt(6) lgkmcnt(0)
	v_mfma_f32_32x32x16_bf16 v[0:15], v[34:37], v[102:105], v[0:15]
	ds_read_b64_tr_b16 v[18:19], v48 offset:35840
	ds_read_b64_tr_b16 v[20:21], v48 offset:37120
	ds_read_b64_tr_b16 v[32:33], v48 offset:37248
	ds_read_b64_tr_b16 v[30:31], v48 offset:35968
	v_add_u32_e32 v34, s23, v47
	v_ashrrev_i32_e32 v35, 31, v34
	s_waitcnt vmcnt(5) lgkmcnt(2)
	v_mfma_f32_32x32x16_bf16 v[0:15], v[18:21], v[106:109], v[0:15]
	v_lshl_add_u32 v18, v46, 7, s22
	v_ashrrev_i32_e32 v19, 31, v18
	v_readlane_b32 s22, v253, 3
	v_lshlrev_b64 v[18:19], 10, v[18:19]
	v_readlane_b32 s23, v253, 4
	s_waitcnt vmcnt(4) lgkmcnt(0)
	v_mfma_f32_32x32x16_bf16 v[0:15], v[30:33], v[110:113], v[0:15]
	v_lshl_add_u64 v[18:19], s[22:23], 0, v[18:19]
	v_lshl_add_u64 v[18:19], v[34:35], 1, v[18:19]
	v_lshl_add_u64 v[16:17], v[18:19], 0, v[16:17]
	s_nop 8
	v_cvt_pk_bf16_f32 v0, v0, v1
	v_cvt_pk_bf16_f32 v1, v2, v3
	v_cvt_pk_bf16_f32 v2, v4, v5
	v_cvt_pk_bf16_f32 v3, v6, v7
	v_cvt_pk_bf16_f32 v4, v8, v9
	v_cvt_pk_bf16_f32 v5, v10, v11
	v_cvt_pk_bf16_f32 v6, v12, v13
	v_cvt_pk_bf16_f32 v7, v14, v15
	v_permlane32_swap_b32_e32 v0, v2
	v_permlane32_swap_b32_e32 v1, v3
	v_permlane32_swap_b32_e32 v4, v6
	v_permlane32_swap_b32_e32 v5, v7
	global_store_dwordx4 v[16:17], v[0:3], off
	global_store_dwordx4 v[16:17], v[4:7], off offset:32
	s_barrier
	s_branch .LBB0_510
